# in-projection GEMM: V^T image tiles assembled in LDS with ds_write_b16 and copied out as 16-byte stores (instead of 128 global_store_short per lane); those tiles moved to the end of the tile sequence
# speedup vs baseline: 1.0025x; 1.0025x over previous
; template <int K, class Epi>
; DI void gemm_phase(unsigned char* lds, int wv, const u16* A, const u16* Bt, int M, int N, Epi& epi) {
;     ...
;       const int L2 = ((G & 7) == 0) ? ((it + 1) * 8 + (b & 7)) * nx + (b >> 3) : (it + 1) * G + b;
;       const bool has_next = L2 < Tmain;
.LBB0_94:
	s_cmpk_lg_u32 s88, 0x100
	s_cbranch_scc0 .Lvt_g256
	s_movk_i32 s6, 0x7fff

; DI u16 f2bf(float a) { return (u16)(pk2(a, 0.f) & 0xffffu); }
;   DI void operator()(f32x4 (&acc)[2][2][4][2], int brow, int bcol, int wr, int wc, int fr, int fq, const int nai) const {
;     ...
;     if (pn == 2 || pn == 6) {
; #pragma unroll
;       for (int ai = 0; ai < 2; ++ai)
; #pragma unroll
;         for (int m = 0; m < 4; ++m) {
;           const int row = brow + ai * 128 + wr * 64 + m * 16 + fr;
;           int b, keypos; keyof(row, b, keypos);
;           const int key = keypos & 63;
; #pragma unroll
;           for (int bj = 0; bj < 2; ++bj) {
;             if (pn == 6 && bj == 0) continue;
;             unsigned char* img = (pn == 2 ? ws + WS_VA + ((size_t)((b * 4 + bj * 2 + hsub) * 36 + (keypos >> 6))) * IMG_TILE
;                                           : ws + WS_VC + ((size_t)((b * 2 + hsub) * 36 + (keypos >> 6))) * IMG_TILE) + (key & 7) * 2;
; #pragma unroll
;             for (int n = 0; n < 2; ++n) {
;               const f32x4 a = acc[ai][bj][m][n];
; #pragma unroll
;               for (int j = 0; j < 4; ++j) {
;                 const int d = dbase + n * 16 + j;
;                 *(u16*)(img + d * 128 + ((((key >> 3)) ^ ((d >> 1) & 7)) << 4)) = f2bf(a[j]);
;               }
;             }
;           }
;         }
;     }
.LBB0_177:
	s_andn2_b64 vcc, exec, s[0:1]
	s_cbranch_vccnz .LBB0_259
	s_cmp_lt_u32 s58, 0x4000
	s_cbranch_scc0 .Lvt_ctxrows
	s_lshr_b32 vcc_lo, s58, 11
	s_bfe_u32 s101, s58, 0x30008
	s_branch .Lvt_c0
.Lvt_ctxrows:
	s_sub_i32 vcc_lo, s58, 0x4000
	s_lshr_b32 vcc_lo, vcc_lo, 8
	s_mov_b32 s101, 8
.Lvt_c0:
	s_cmp_eq_u32 s23, 2
	s_cselect_b32 s100, s54, s52
	s_cselect_b32 vcc_hi, 36, 18
	s_mul_i32 vcc_lo, vcc_lo, vcc_hi
	s_add_i32 s101, s101, vcc_lo
	v_or_b32_e32 v0, s58, v155
	v_add_u32_e32 v73, v0, v156
	v_cmp_lt_i32_e32 vcc, s9, v73
	s_and_saveexec_b64 s[0:1], vcc
	s_xor_b64 s[0:1], exec, s[0:1]
	v_add_u32_e32 v0, 0xffffc000, v73
	v_and_b32_e32 v6, 0xcf, v73
	v_lshrrev_b32_e32 v0, 8, v0
	v_or_b32_e32 v10, 0x800, v6
	s_or_saveexec_b64 s[0:1], s[0:1]
	v_ashrrev_i32_e32 v130, 11, v73
	s_movk_i32 s5, 0x48
	s_xor_b64 exec, exec, s[0:1]
	v_ashrrev_i32_e32 v0, 11, v73
	v_and_b32_e32 v10, 0x7cf, v73
	s_or_b64 exec, exec, s[0:1]
	v_lshl_or_b32 v7, v0, 1, v126
	v_lshrrev_b32_e32 v6, 6, v10
	s_cmp_eq_u32 s4, 8
	v_mad_u64_u32 v[8:9], s[2:3], v7, 36, v[6:7]
	s_cselect_b64 s[0:1], -1, 0
	v_ashrrev_i32_e32 v9, 31, v8
	v_lshl_or_b32 v7, v0, 2, v126
	v_lshlrev_b32_e32 v0, 1, v10
	v_lshrrev_b32_e32 v72, 3, v10
	v_cndmask_b32_e64 v10, 0, 1, s[62:63]
	v_lshlrev_b64 v[8:9], 13, v[8:9]
	v_cmp_ne_u32_e64 s[38:39], 1, v10
	v_cndmask_b32_e64 v10, 0, 1, s[0:1]
	v_lshl_add_u64 v[8:9], s[52:53], 0, v[8:9]
	v_and_b32_e32 v0, 14, v0
	s_andn2_b64 vcc, exec, s[62:63]
	v_cmp_ne_u32_e64 s[36:37], 1, v10
	s_cbranch_vccnz .LBB0_186
	s_and_b64 vcc, exec, s[36:37]
	v_mov_b64_e32 v[10:11], v[8:9]
	s_cbranch_vccnz .LBB0_185
	v_mad_u64_u32 v[10:11], s[0:1], v7, 36, v[6:7]
	v_ashrrev_i32_e32 v11, 31, v10
	v_lshlrev_b64 v[10:11], 13, v[10:11]
	v_lshl_add_u64 v[10:11], s[54:55], 0, v[10:11]
.LBB0_185:
	v_subrev_u32_e32 v196, s100, v10
	v_and_b32_e32 v197, 0x7fff, v196
	v_lshrrev_b32_e32 v196, 15, v196
	v_subrev_u32_e32 v196, s101, v196
	v_mul_u32_u24_e32 v196, 57, v196
	v_lshrrev_b32_e32 v196, 9, v196
	v_lshl_add_u32 v10, v196, 15, v197
	v_mov_b32_e32 v11, 0
	v_lshrrev_b32_e32 v76, 1, v127
	v_xor_b32_e32 v76, v72, v76
	v_lshl_add_u64 v[10:11], v[10:11], 0, v[0:1]
	v_lshlrev_b32_e32 v12, 7, v127
	v_mov_b32_e32 v13, v1
	v_lshlrev_b32_e32 v76, 4, v76
	v_lshl_add_u64 v[12:13], v[10:11], 0, v[12:13]
	v_and_b32_e32 v76, 0x70, v76
	v_mov_b32_e32 v77, v1
	v_cvt_pk_bf16_f32 v80, v140, s0
	v_lshl_add_u64 v[12:13], v[12:13], 0, v[76:77]
	ds_write_b16 v12, v80
	v_cvt_pk_bf16_f32 v76, v141, s0
	v_or_b32_e32 v80, 2, v127
	ds_write_b16 v12, v76 offset:128
	v_lshlrev_b32_e32 v76, 7, v80
	v_lshrrev_b32_e32 v80, 1, v80
	v_xor_b32_e32 v80, v72, v80
	v_lshlrev_b32_e32 v80, 4, v80
	v_lshl_add_u64 v[76:77], v[10:11], 0, v[76:77]
	v_and_b32_e32 v80, 0x70, v80
	v_mov_b32_e32 v81, v1
	v_cvt_pk_bf16_f32 v84, v162, s0
	v_lshl_add_u64 v[76:77], v[76:77], 0, v[80:81]
	v_or_b32_e32 v80, 3, v127
	ds_write_b16 v76, v84
	v_lshlrev_b32_e32 v76, 7, v80
	v_lshrrev_b32_e32 v80, 1, v80
	v_xor_b32_e32 v80, v72, v80
	v_mov_b32_e32 v77, v1
	v_lshlrev_b32_e32 v80, 4, v80
	v_lshl_add_u64 v[76:77], v[10:11], 0, v[76:77]
	v_and_b32_e32 v80, 0x70, v80
	v_cvt_pk_bf16_f32 v84, v119, s0
	v_lshl_add_u64 v[76:77], v[76:77], 0, v[80:81]
	ds_write_b16 v76, v84
	v_cvt_pk_bf16_f32 v76, v138, s0
	ds_write_b16 v12, v76 offset:2048
	v_cvt_pk_bf16_f32 v76, v139, s0
	ds_write_b16 v12, v76 offset:2176
	v_or_b32_e32 v76, 18, v127
	v_lshlrev_b32_e32 v12, 7, v76
	v_lshrrev_b32_e32 v76, 1, v76
	v_xor_b32_e32 v76, v72, v76
	v_mov_b32_e32 v13, v1
	v_lshlrev_b32_e32 v76, 4, v76
	v_lshl_add_u64 v[12:13], v[10:11], 0, v[12:13]
	v_and_b32_e32 v76, 0x70, v76
	v_mov_b32_e32 v77, v1
	v_cvt_pk_bf16_f32 v80, v161, s0
	v_lshl_add_u64 v[12:13], v[12:13], 0, v[76:77]
	v_or_b32_e32 v76, 19, v127
	ds_write_b16 v12, v80
	v_lshlrev_b32_e32 v12, 7, v76
	v_mov_b32_e32 v13, v1
	v_lshl_add_u64 v[10:11], v[10:11], 0, v[12:13]
	v_lshrrev_b32_e32 v12, 1, v76
	v_xor_b32_e32 v12, v72, v12
	v_lshlrev_b32_e32 v12, 4, v12
	v_and_b32_e32 v12, 0x70, v12
	v_cvt_pk_bf16_f32 v77, v118, s0
	v_lshl_add_u64 v[10:11], v[10:11], 0, v[12:13]
	ds_write_b16 v10, v77

; DI u16 f2bf(float a) { return (u16)(pk2(a, 0.f) & 0xffffu); }
;   DI void operator()(f32x4 (&acc)[2][2][4][2], int brow, int bcol, int wr, int wc, int fr, int fq, const int nai) const {
;     ...
;     if (pn == 2 || pn == 6) {
; #pragma unroll
;       for (int ai = 0; ai < 2; ++ai)
; #pragma unroll
;         for (int m = 0; m < 4; ++m) {
;           const int row = brow + ai * 128 + wr * 64 + m * 16 + fr;
;           int b, keypos; keyof(row, b, keypos);
;           const int key = keypos & 63;
; #pragma unroll
;           for (int bj = 0; bj < 2; ++bj) {
;             if (pn == 6 && bj == 0) continue;
;             unsigned char* img = (pn == 2 ? ws + WS_VA + ((size_t)((b * 4 + bj * 2 + hsub) * 36 + (keypos >> 6))) * IMG_TILE
;                                           : ws + WS_VC + ((size_t)((b * 2 + hsub) * 36 + (keypos >> 6))) * IMG_TILE) + (key & 7) * 2;
; #pragma unroll
;             for (int n = 0; n < 2; ++n) {
;               const f32x4 a = acc[ai][bj][m][n];
; #pragma unroll
;               for (int j = 0; j < 4; ++j) {
;                 const int d = dbase + n * 16 + j;
;                 *(u16*)(img + d * 128 + ((((key >> 3)) ^ ((d >> 1) & 7)) << 4)) = f2bf(a[j]);
;               }
;             }
;           }
;         }
;     }
.LBB0_188:
	v_subrev_u32_e32 v196, s100, v8
	v_and_b32_e32 v197, 0x7fff, v196
	v_lshrrev_b32_e32 v196, 15, v196
	v_subrev_u32_e32 v196, s101, v196
	v_mul_u32_u24_e32 v196, 57, v196
	v_lshrrev_b32_e32 v196, 9, v196
	v_lshl_add_u32 v8, v196, 15, v197
	v_mov_b32_e32 v9, 0
	v_lshrrev_b32_e32 v116, 1, v127
	v_lshl_add_u64 v[76:77], v[8:9], 0, v[0:1]
	v_xor_b32_e32 v8, v72, v116
	v_lshlrev_b32_e32 v0, 7, v127
	v_lshlrev_b32_e32 v8, 4, v8
	v_lshl_add_u64 v[6:7], v[76:77], 0, v[0:1]
	v_and_b32_e32 v8, 0x70, v8
	v_mov_b32_e32 v9, v1
	v_cvt_pk_bf16_f32 v12, v112, s0
	v_lshl_add_u64 v[10:11], v[6:7], 0, v[8:9]
	ds_write_b16 v10, v12
	v_or_b32_e32 v12, 2, v127
	v_cvt_pk_bf16_f32 v6, v113, s0
	v_lshrrev_b32_e32 v117, 1, v12
	ds_write_b16 v10, v6 offset:128
	v_lshlrev_b32_e32 v6, 7, v12
	v_xor_b32_e32 v12, v72, v117
	v_mov_b32_e32 v7, v1
	v_lshlrev_b32_e32 v12, 4, v12
	v_lshl_add_u64 v[8:9], v[76:77], 0, v[6:7]
	v_and_b32_e32 v12, 0x70, v12
	v_mov_b32_e32 v13, v1
	v_cvt_pk_bf16_f32 v80, v114, s0
	v_lshl_add_u64 v[8:9], v[8:9], 0, v[12:13]
	ds_write_b16 v8, v80
	v_or_b32_e32 v80, 3, v127
	v_lshrrev_b32_e32 v122, 1, v80
	v_lshlrev_b32_e32 v8, 7, v80
	v_xor_b32_e32 v80, v72, v122
	v_mov_b32_e32 v9, v1
	v_lshlrev_b32_e32 v80, 4, v80
	v_lshl_add_u64 v[12:13], v[76:77], 0, v[8:9]
	v_and_b32_e32 v80, 0x70, v80
	v_mov_b32_e32 v81, v1
	v_cvt_pk_bf16_f32 v84, v115, s0
	v_lshl_add_u64 v[12:13], v[12:13], 0, v[80:81]
	ds_write_b16 v12, v84
	v_cvt_pk_bf16_f32 v12, v108, s0
	v_or_b32_e32 v80, 18, v127
	ds_write_b16 v10, v12 offset:2048
	v_cvt_pk_bf16_f32 v12, v109, s0
	v_lshrrev_b32_e32 v123, 1, v80
	ds_write_b16 v10, v12 offset:2176
	v_lshlrev_b32_e32 v10, 7, v80
	v_xor_b32_e32 v80, v72, v123
	v_mov_b32_e32 v11, v1
	v_lshlrev_b32_e32 v80, 4, v80
	v_lshl_add_u64 v[12:13], v[76:77], 0, v[10:11]
	v_and_b32_e32 v80, 0x70, v80
	v_lshl_add_u64 v[12:13], v[12:13], 0, v[80:81]
	v_or_b32_e32 v80, 19, v127
	v_lshrrev_b32_e32 v127, 1, v80
	v_cvt_pk_bf16_f32 v84, v82, s0
	v_xor_b32_e32 v72, v72, v127
	ds_write_b16 v12, v84
	v_lshlrev_b32_e32 v12, 7, v80
	v_mov_b32_e32 v13, v1
	v_lshlrev_b32_e32 v72, 4, v72
	v_lshl_add_u64 v[76:77], v[76:77], 0, v[12:13]
	v_and_b32_e32 v80, 0x70, v72
	v_or_b32_e32 v72, 16, v73
	v_cvt_pk_bf16_f32 v84, v83, s0
	v_lshl_add_u64 v[76:77], v[76:77], 0, v[80:81]
	v_cmp_lt_i32_e32 vcc, s9, v72
	ds_write_b16 v76, v84
	s_and_saveexec_b64 s[0:1], vcc
	s_xor_b64 s[0:1], exec, s[0:1]
	v_add_u32_e32 v76, 0xffffc010, v73
	v_and_b32_e32 v72, 0xdf, v72
	v_lshrrev_b32_e32 v76, 8, v76
	v_or_b32_e32 v84, 0x800, v72
	s_andn2_saveexec_b64 s[0:1], s[0:1]
	v_ashrrev_i32_e32 v76, 11, v73
	v_and_b32_e32 v84, 0x7df, v72
	s_or_b64 exec, exec, s[0:1]
	v_lshl_or_b32 v77, v76, 1, v126
	v_lshrrev_b32_e32 v72, 6, v84
	v_mad_u64_u32 v[80:81], s[0:1], v77, 36, v[72:73]
	v_ashrrev_i32_e32 v81, 31, v80
	v_lshlrev_b64 v[80:81], 13, v[80:81]
	v_lshl_or_b32 v132, v76, 2, v126
	v_lshlrev_b32_e32 v76, 1, v84
	v_lshl_add_u64 v[80:81], s[52:53], 0, v[80:81]
	v_and_b32_e32 v76, 14, v76
	v_mov_b32_e32 v77, v1
	s_and_b64 vcc, exec, s[38:39]
	v_lshrrev_b32_e32 v131, 3, v84
	s_cbranch_vccnz .LBB0_196
	s_and_b64 vcc, exec, s[36:37]
	v_mov_b64_e32 v[84:85], v[80:81]
	s_cbranch_vccnz .LBB0_195
	v_mad_u64_u32 v[84:85], s[0:1], v132, 36, v[72:73]
	v_ashrrev_i32_e32 v85, 31, v84
	v_lshlrev_b64 v[84:85], 13, v[84:85]
	v_lshl_add_u64 v[84:85], s[54:55], 0, v[84:85]
.LBB0_195:
	v_subrev_u32_e32 v196, s100, v84
	v_and_b32_e32 v197, 0x7fff, v196
	v_lshrrev_b32_e32 v196, 15, v196
	v_subrev_u32_e32 v196, s101, v196
	v_mul_u32_u24_e32 v196, 57, v196
	v_lshrrev_b32_e32 v196, 9, v196
	v_lshl_add_u32 v84, v196, 15, v197
	v_mov_b32_e32 v85, 0
	v_xor_b32_e32 v163, v131, v116
	v_lshl_add_u64 v[84:85], v[84:85], 0, v[76:77]
	v_lshlrev_b32_e32 v163, 4, v163
	v_lshl_add_u64 v[164:165], v[84:85], 0, v[0:1]
	v_and_b32_e32 v166, 0x70, v163
	v_mov_b32_e32 v167, v1
	v_xor_b32_e32 v163, v131, v117
	v_cvt_pk_bf16_f32 v133, v136, s0
	v_lshl_add_u64 v[164:165], v[164:165], 0, v[166:167]
	v_lshlrev_b32_e32 v163, 4, v163
	ds_write_b16 v164, v133
	v_cvt_pk_bf16_f32 v133, v137, s0
	v_lshl_add_u64 v[166:167], v[84:85], 0, v[6:7]
	v_and_b32_e32 v168, 0x70, v163
	v_mov_b32_e32 v169, v1
	v_xor_b32_e32 v163, v131, v122
	ds_write_b16 v164, v133 offset:128
	v_cvt_pk_bf16_f32 v133, v160, s0
	v_lshl_add_u64 v[166:167], v[166:167], 0, v[168:169]
	v_lshlrev_b32_e32 v163, 4, v163
	ds_write_b16 v166, v133
	v_lshl_add_u64 v[166:167], v[84:85], 0, v[8:9]
	v_and_b32_e32 v168, 0x70, v163
	v_cvt_pk_bf16_f32 v133, v111, s0
	v_lshl_add_u64 v[166:167], v[166:167], 0, v[168:169]
	ds_write_b16 v166, v133
	v_cvt_pk_bf16_f32 v133, v134, s0
	v_xor_b32_e32 v163, v131, v123
	ds_write_b16 v164, v133 offset:2048
	v_cvt_pk_bf16_f32 v133, v135, s0
	v_lshlrev_b32_e32 v163, 4, v163
	ds_write_b16 v164, v133 offset:2176
	v_lshl_add_u64 v[164:165], v[84:85], 0, v[10:11]
	v_and_b32_e32 v166, 0x70, v163
	v_mov_b32_e32 v167, v1
	v_xor_b32_e32 v163, v131, v127
	v_cvt_pk_bf16_f32 v133, v157, s0
	v_lshl_add_u64 v[164:165], v[164:165], 0, v[166:167]
	v_lshlrev_b32_e32 v163, 4, v163
	ds_write_b16 v164, v133
	v_lshl_add_u64 v[84:85], v[84:85], 0, v[12:13]
	v_and_b32_e32 v164, 0x70, v163
	v_mov_b32_e32 v165, v1
	v_cvt_pk_bf16_f32 v133, v110, s0
	v_lshl_add_u64 v[84:85], v[84:85], 0, v[164:165]
	ds_write_b16 v84, v133

; DI u16 f2bf(float a) { return (u16)(pk2(a, 0.f) & 0xffffu); }
;   DI void operator()(f32x4 (&acc)[2][2][4][2], int brow, int bcol, int wr, int wc, int fr, int fq, const int nai) const {
;     ...
;     if (pn == 2 || pn == 6) {
; #pragma unroll
;       for (int ai = 0; ai < 2; ++ai)
; #pragma unroll
;         for (int m = 0; m < 4; ++m) {
;           const int row = brow + ai * 128 + wr * 64 + m * 16 + fr;
;           int b, keypos; keyof(row, b, keypos);
;           const int key = keypos & 63;
; #pragma unroll
;           for (int bj = 0; bj < 2; ++bj) {
;             if (pn == 6 && bj == 0) continue;
;             unsigned char* img = (pn == 2 ? ws + WS_VA + ((size_t)((b * 4 + bj * 2 + hsub) * 36 + (keypos >> 6))) * IMG_TILE
;                                           : ws + WS_VC + ((size_t)((b * 2 + hsub) * 36 + (keypos >> 6))) * IMG_TILE) + (key & 7) * 2;
; #pragma unroll
;             for (int n = 0; n < 2; ++n) {
;               const f32x4 a = acc[ai][bj][m][n];
; #pragma unroll
;               for (int j = 0; j < 4; ++j) {
;                 const int d = dbase + n * 16 + j;
;                 *(u16*)(img + d * 128 + ((((key >> 3)) ^ ((d >> 1) & 7)) << 4)) = f2bf(a[j]);
;               }
;             }
;           }
;         }
;     }
.LBB0_198:
	v_subrev_u32_e32 v196, s100, v80
	v_and_b32_e32 v197, 0x7fff, v196
	v_lshrrev_b32_e32 v196, 15, v196
	v_subrev_u32_e32 v196, s101, v196
	v_mul_u32_u24_e32 v196, 57, v196
	v_lshrrev_b32_e32 v196, 9, v196
	v_lshl_add_u32 v80, v196, 15, v197
	v_mov_b32_e32 v81, 0
	v_xor_b32_e32 v84, v131, v116
	v_lshl_add_u64 v[76:77], v[80:81], 0, v[76:77]
	v_lshlrev_b32_e32 v84, 4, v84
	v_xor_b32_e32 v132, v131, v117
	v_lshl_add_u64 v[80:81], v[76:77], 0, v[0:1]
	v_and_b32_e32 v84, 0x70, v84
	v_mov_b32_e32 v85, v1
	v_lshlrev_b32_e32 v132, 4, v132
	v_cvt_pk_bf16_f32 v72, v104, s0
	v_lshl_add_u64 v[80:81], v[80:81], 0, v[84:85]
	v_lshl_add_u64 v[84:85], v[76:77], 0, v[6:7]
	v_and_b32_e32 v132, 0x70, v132
	v_mov_b32_e32 v133, v1
	ds_write_b16 v80, v72
	v_cvt_pk_bf16_f32 v72, v105, s0
	v_lshl_add_u64 v[84:85], v[84:85], 0, v[132:133]
	v_xor_b32_e32 v132, v131, v122
	ds_write_b16 v80, v72 offset:128
	v_cvt_pk_bf16_f32 v72, v106, s0
	v_lshlrev_b32_e32 v132, 4, v132
	ds_write_b16 v84, v72
	v_lshl_add_u64 v[84:85], v[76:77], 0, v[8:9]
	v_and_b32_e32 v132, 0x70, v132
	v_cvt_pk_bf16_f32 v72, v107, s0
	v_lshl_add_u64 v[84:85], v[84:85], 0, v[132:133]
	ds_write_b16 v84, v72
	v_cvt_pk_bf16_f32 v72, v100, s0
	v_xor_b32_e32 v84, v131, v123
	ds_write_b16 v80, v72 offset:2048
	v_cvt_pk_bf16_f32 v72, v101, s0
	v_lshlrev_b32_e32 v84, 4, v84
	ds_write_b16 v80, v72 offset:2176
	v_lshl_add_u64 v[80:81], v[76:77], 0, v[10:11]
	v_and_b32_e32 v84, 0x70, v84
	v_mov_b32_e32 v85, v1
	v_cvt_pk_bf16_f32 v72, v78, s0
	v_lshl_add_u64 v[80:81], v[80:81], 0, v[84:85]
	ds_write_b16 v80, v72
	v_xor_b32_e32 v80, v131, v127
	v_lshlrev_b32_e32 v80, 4, v80
	v_lshl_add_u64 v[76:77], v[76:77], 0, v[12:13]
	v_and_b32_e32 v80, 0x70, v80
	v_mov_b32_e32 v81, v1
	v_cvt_pk_bf16_f32 v72, v79, s0
	v_lshl_add_u64 v[76:77], v[76:77], 0, v[80:81]
	ds_write_b16 v76, v72
	v_or_b32_e32 v72, 32, v73
	v_cmp_lt_i32_e32 vcc, s9, v72
	s_and_saveexec_b64 s[0:1], vcc
	s_xor_b64 s[0:1], exec, s[0:1]
	v_add_u32_e32 v76, 0xffffc020, v73
	v_and_b32_e32 v72, 0xef, v72
	v_lshrrev_b32_e32 v76, 8, v76
	v_or_b32_e32 v84, 0x800, v72
	s_andn2_saveexec_b64 s[0:1], s[0:1]
	v_ashrrev_i32_e32 v76, 11, v73
	v_and_b32_e32 v84, 0x7ef, v72
	s_or_b64 exec, exec, s[0:1]
	v_lshl_or_b32 v77, v76, 1, v126
	v_lshrrev_b32_e32 v72, 6, v84
	v_mad_u64_u32 v[80:81], s[0:1], v77, 36, v[72:73]
	v_ashrrev_i32_e32 v81, 31, v80
	v_lshlrev_b64 v[80:81], 13, v[80:81]
	v_lshl_or_b32 v132, v76, 2, v126
	v_lshlrev_b32_e32 v76, 1, v84
	v_lshl_add_u64 v[80:81], s[52:53], 0, v[80:81]
	v_and_b32_e32 v76, 14, v76
	v_mov_b32_e32 v77, v1
	s_and_b64 vcc, exec, s[38:39]
	v_lshrrev_b32_e32 v131, 3, v84
	s_cbranch_vccnz .LBB0_206
	s_and_b64 vcc, exec, s[36:37]
	v_mov_b64_e32 v[84:85], v[80:81]
	s_cbranch_vccnz .LBB0_205
	v_mad_u64_u32 v[84:85], s[0:1], v132, 36, v[72:73]
	v_ashrrev_i32_e32 v85, 31, v84
	v_lshlrev_b64 v[84:85], 13, v[84:85]
	v_lshl_add_u64 v[84:85], s[54:55], 0, v[84:85]
.LBB0_205:
	v_subrev_u32_e32 v196, s100, v84
	v_and_b32_e32 v197, 0x7fff, v196
	v_lshrrev_b32_e32 v196, 15, v196
	v_subrev_u32_e32 v196, s101, v196
	v_mul_u32_u24_e32 v196, 57, v196
	v_lshrrev_b32_e32 v196, 9, v196
	v_lshl_add_u32 v84, v196, 15, v197
	v_mov_b32_e32 v85, 0
	v_xor_b32_e32 v163, v131, v116
	v_lshl_add_u64 v[84:85], v[84:85], 0, v[76:77]
	v_lshlrev_b32_e32 v163, 4, v163
	v_lshl_add_u64 v[164:165], v[84:85], 0, v[0:1]
	v_and_b32_e32 v166, 0x70, v163
	v_mov_b32_e32 v167, v1
	v_xor_b32_e32 v163, v131, v117
	v_cvt_pk_bf16_f32 v133, v128, s0
	v_lshl_add_u64 v[164:165], v[164:165], 0, v[166:167]
	v_lshlrev_b32_e32 v163, 4, v163
	ds_write_b16 v164, v133
	v_cvt_pk_bf16_f32 v133, v129, s0
	v_lshl_add_u64 v[166:167], v[84:85], 0, v[6:7]
	v_and_b32_e32 v168, 0x70, v163
	v_mov_b32_e32 v169, v1
	v_xor_b32_e32 v163, v131, v122
	ds_write_b16 v164, v133 offset:128
	v_cvt_pk_bf16_f32 v133, v153, s0
	v_lshl_add_u64 v[166:167], v[166:167], 0, v[168:169]
	v_lshlrev_b32_e32 v163, 4, v163
	ds_write_b16 v166, v133
	v_lshl_add_u64 v[166:167], v[84:85], 0, v[8:9]
	v_and_b32_e32 v168, 0x70, v163
	v_cvt_pk_bf16_f32 v133, v103, s0
	v_lshl_add_u64 v[166:167], v[166:167], 0, v[168:169]
	ds_write_b16 v166, v133
	v_cvt_pk_bf16_f32 v133, v124, s0
	v_xor_b32_e32 v163, v131, v123
	ds_write_b16 v164, v133 offset:2048
	v_cvt_pk_bf16_f32 v133, v125, s0
	v_lshlrev_b32_e32 v163, 4, v163
	ds_write_b16 v164, v133 offset:2176
	v_lshl_add_u64 v[164:165], v[84:85], 0, v[10:11]
	v_and_b32_e32 v166, 0x70, v163
	v_mov_b32_e32 v167, v1
	v_xor_b32_e32 v163, v131, v127
	v_cvt_pk_bf16_f32 v133, v152, s0
	v_lshl_add_u64 v[164:165], v[164:165], 0, v[166:167]
	v_lshlrev_b32_e32 v163, 4, v163
	ds_write_b16 v164, v133
	v_lshl_add_u64 v[84:85], v[84:85], 0, v[12:13]
	v_and_b32_e32 v164, 0x70, v163
	v_mov_b32_e32 v165, v1
	v_cvt_pk_bf16_f32 v133, v102, s0
	v_lshl_add_u64 v[84:85], v[84:85], 0, v[164:165]
	ds_write_b16 v84, v133

; DI u16 f2bf(float a) { return (u16)(pk2(a, 0.f) & 0xffffu); }
;   DI void operator()(f32x4 (&acc)[2][2][4][2], int brow, int bcol, int wr, int wc, int fr, int fq, const int nai) const {
;     ...
;     if (pn == 2 || pn == 6) {
; #pragma unroll
;       for (int ai = 0; ai < 2; ++ai)
; #pragma unroll
;         for (int m = 0; m < 4; ++m) {
;           const int row = brow + ai * 128 + wr * 64 + m * 16 + fr;
;           int b, keypos; keyof(row, b, keypos);
;           const int key = keypos & 63;
; #pragma unroll
;           for (int bj = 0; bj < 2; ++bj) {
;             if (pn == 6 && bj == 0) continue;
;             unsigned char* img = (pn == 2 ? ws + WS_VA + ((size_t)((b * 4 + bj * 2 + hsub) * 36 + (keypos >> 6))) * IMG_TILE
;                                           : ws + WS_VC + ((size_t)((b * 2 + hsub) * 36 + (keypos >> 6))) * IMG_TILE) + (key & 7) * 2;
; #pragma unroll
;             for (int n = 0; n < 2; ++n) {
;               const f32x4 a = acc[ai][bj][m][n];
; #pragma unroll
;               for (int j = 0; j < 4; ++j) {
;                 const int d = dbase + n * 16 + j;
;                 *(u16*)(img + d * 128 + ((((key >> 3)) ^ ((d >> 1) & 7)) << 4)) = f2bf(a[j]);
;               }
;             }
;           }
;         }
;     }
.LBB0_208:
	v_subrev_u32_e32 v196, s100, v80
	v_and_b32_e32 v197, 0x7fff, v196
	v_lshrrev_b32_e32 v196, 15, v196
	v_subrev_u32_e32 v196, s101, v196
	v_mul_u32_u24_e32 v196, 57, v196
	v_lshrrev_b32_e32 v196, 9, v196
	v_lshl_add_u32 v80, v196, 15, v197
	v_mov_b32_e32 v81, 0
	v_xor_b32_e32 v84, v131, v116
	v_lshl_add_u64 v[76:77], v[80:81], 0, v[76:77]
	v_lshlrev_b32_e32 v84, 4, v84
	v_xor_b32_e32 v132, v131, v117
	v_lshl_add_u64 v[80:81], v[76:77], 0, v[0:1]
	v_and_b32_e32 v84, 0x70, v84
	v_mov_b32_e32 v85, v1
	v_lshlrev_b32_e32 v132, 4, v132
	v_cvt_pk_bf16_f32 v72, v96, s0
	v_lshl_add_u64 v[80:81], v[80:81], 0, v[84:85]
	v_lshl_add_u64 v[84:85], v[76:77], 0, v[6:7]
	v_and_b32_e32 v132, 0x70, v132
	v_mov_b32_e32 v133, v1
	ds_write_b16 v80, v72
	v_cvt_pk_bf16_f32 v72, v97, s0
	v_lshl_add_u64 v[84:85], v[84:85], 0, v[132:133]
	v_xor_b32_e32 v132, v131, v122
	ds_write_b16 v80, v72 offset:128
	v_cvt_pk_bf16_f32 v72, v98, s0
	v_lshlrev_b32_e32 v132, 4, v132
	ds_write_b16 v84, v72
	v_lshl_add_u64 v[84:85], v[76:77], 0, v[8:9]
	v_and_b32_e32 v132, 0x70, v132
	v_cvt_pk_bf16_f32 v72, v99, s0
	v_lshl_add_u64 v[84:85], v[84:85], 0, v[132:133]
	ds_write_b16 v84, v72
	v_cvt_pk_bf16_f32 v72, v92, s0
	v_xor_b32_e32 v84, v131, v123
	ds_write_b16 v80, v72 offset:2048
	v_cvt_pk_bf16_f32 v72, v93, s0
	v_lshlrev_b32_e32 v84, 4, v84
	ds_write_b16 v80, v72 offset:2176
	v_lshl_add_u64 v[80:81], v[76:77], 0, v[10:11]
	v_and_b32_e32 v84, 0x70, v84
	v_mov_b32_e32 v85, v1
	v_cvt_pk_bf16_f32 v72, v74, s0
	v_lshl_add_u64 v[80:81], v[80:81], 0, v[84:85]
	ds_write_b16 v80, v72
	v_xor_b32_e32 v80, v131, v127
	v_lshlrev_b32_e32 v80, 4, v80
	v_lshl_add_u64 v[76:77], v[76:77], 0, v[12:13]
	v_and_b32_e32 v80, 0x70, v80
	v_mov_b32_e32 v81, v1
	v_cvt_pk_bf16_f32 v72, v75, s0
	v_lshl_add_u64 v[76:77], v[76:77], 0, v[80:81]
	ds_write_b16 v76, v72
	v_or_b32_e32 v72, 48, v73
	v_cmp_lt_i32_e32 vcc, s9, v72
	s_and_saveexec_b64 s[0:1], vcc
	s_xor_b64 s[0:1], exec, s[0:1]
	v_add_u32_e32 v76, 0xffffc030, v73
	s_movk_i32 s2, 0x800
	v_lshrrev_b32_e32 v130, 8, v76
	v_or_b32_sdwa v84, v72, s2 dst_sel:DWORD dst_unused:UNUSED_PAD src0_sel:BYTE_0 src1_sel:DWORD
	s_andn2_saveexec_b64 s[0:1], s[0:1]
	v_and_b32_e32 v84, 0x7ff, v72
	s_or_b64 exec, exec, s[0:1]
	v_lshl_or_b32 v76, v130, 1, v126
	v_lshrrev_b32_e32 v72, 6, v84
	v_mad_u64_u32 v[76:77], s[0:1], v76, 36, v[72:73]
	v_ashrrev_i32_e32 v77, 31, v76
	v_lshlrev_b64 v[76:77], 13, v[76:77]
	v_lshl_add_u64 v[80:81], s[52:53], 0, v[76:77]
	v_lshlrev_b32_e32 v76, 1, v84
	v_lshl_or_b32 v131, v130, 2, v126
	v_and_b32_e32 v76, 14, v76
	v_mov_b32_e32 v77, v1
	s_and_b64 vcc, exec, s[38:39]
	v_lshrrev_b32_e32 v130, 3, v84
	s_cbranch_vccnz .LBB0_216
	s_and_b64 vcc, exec, s[36:37]
	v_mov_b64_e32 v[84:85], v[80:81]
	s_cbranch_vccnz .LBB0_215
	v_mad_u64_u32 v[84:85], s[0:1], v131, 36, v[72:73]
	v_ashrrev_i32_e32 v85, 31, v84
	v_lshlrev_b64 v[84:85], 13, v[84:85]
	v_lshl_add_u64 v[84:85], s[54:55], 0, v[84:85]
.LBB0_215:
	v_subrev_u32_e32 v196, s100, v84
	v_and_b32_e32 v197, 0x7fff, v196
	v_lshrrev_b32_e32 v196, 15, v196
	v_subrev_u32_e32 v196, s101, v196
	v_mul_u32_u24_e32 v196, 57, v196
	v_lshrrev_b32_e32 v196, 9, v196
	v_lshl_add_u32 v84, v196, 15, v197
	v_mov_b32_e32 v85, 0
	v_xor_b32_e32 v164, v130, v116
	v_lshl_add_u64 v[84:85], v[84:85], 0, v[76:77]
	v_lshlrev_b32_e32 v164, 4, v164
	v_xor_b32_e32 v166, v130, v117
	v_lshl_add_u64 v[132:133], v[84:85], 0, v[0:1]
	v_and_b32_e32 v164, 0x70, v164
	v_mov_b32_e32 v165, v1
	v_lshlrev_b32_e32 v166, 4, v166
	v_cvt_pk_bf16_f32 v163, v120, s0
	v_lshl_add_u64 v[132:133], v[132:133], 0, v[164:165]
	v_lshl_add_u64 v[164:165], v[84:85], 0, v[6:7]
	v_and_b32_e32 v166, 0x70, v166
	v_mov_b32_e32 v167, v1
	ds_write_b16 v132, v163
	v_cvt_pk_bf16_f32 v163, v121, s0
	v_lshl_add_u64 v[164:165], v[164:165], 0, v[166:167]
	v_xor_b32_e32 v166, v130, v122
	ds_write_b16 v132, v163 offset:128
	v_cvt_pk_bf16_f32 v163, v151, s0
	v_lshlrev_b32_e32 v166, 4, v166
	ds_write_b16 v164, v163
	v_lshl_add_u64 v[164:165], v[84:85], 0, v[8:9]
	v_and_b32_e32 v166, 0x70, v166
	v_cvt_pk_bf16_f32 v163, v95, s0
	v_lshl_add_u64 v[164:165], v[164:165], 0, v[166:167]
	ds_write_b16 v164, v163
	v_cvt_pk_bf16_f32 v163, v68, s0
	v_xor_b32_e32 v164, v130, v123
	ds_write_b16 v132, v163 offset:2048
	v_cvt_pk_bf16_f32 v163, v69, s0
	v_lshlrev_b32_e32 v164, 4, v164
	ds_write_b16 v132, v163 offset:2176
	v_lshl_add_u64 v[132:133], v[84:85], 0, v[10:11]
	v_and_b32_e32 v164, 0x70, v164
	v_mov_b32_e32 v165, v1
	v_cvt_pk_bf16_f32 v163, v150, s0
	v_lshl_add_u64 v[132:133], v[132:133], 0, v[164:165]
	ds_write_b16 v132, v163
	v_xor_b32_e32 v132, v130, v127
	v_lshlrev_b32_e32 v132, 4, v132
	v_lshl_add_u64 v[84:85], v[84:85], 0, v[12:13]
	v_and_b32_e32 v132, 0x70, v132
	v_mov_b32_e32 v133, v1
	v_cvt_pk_bf16_f32 v163, v94, s0
	v_lshl_add_u64 v[84:85], v[84:85], 0, v[132:133]
	ds_write_b16 v84, v163

; DI u16 f2bf(float a) { return (u16)(pk2(a, 0.f) & 0xffffu); }
;   DI void operator()(f32x4 (&acc)[2][2][4][2], int brow, int bcol, int wr, int wc, int fr, int fq, const int nai) const {
;     ...
;     if (pn == 2 || pn == 6) {
; #pragma unroll
;       for (int ai = 0; ai < 2; ++ai)
; #pragma unroll
;         for (int m = 0; m < 4; ++m) {
;           const int row = brow + ai * 128 + wr * 64 + m * 16 + fr;
;           int b, keypos; keyof(row, b, keypos);
;           const int key = keypos & 63;
; #pragma unroll
;           for (int bj = 0; bj < 2; ++bj) {
;             if (pn == 6 && bj == 0) continue;
;             unsigned char* img = (pn == 2 ? ws + WS_VA + ((size_t)((b * 4 + bj * 2 + hsub) * 36 + (keypos >> 6))) * IMG_TILE
;                                           : ws + WS_VC + ((size_t)((b * 2 + hsub) * 36 + (keypos >> 6))) * IMG_TILE) + (key & 7) * 2;
; #pragma unroll
;             for (int n = 0; n < 2; ++n) {
;               const f32x4 a = acc[ai][bj][m][n];
; #pragma unroll
;               for (int j = 0; j < 4; ++j) {
;                 const int d = dbase + n * 16 + j;
;                 *(u16*)(img + d * 128 + ((((key >> 3)) ^ ((d >> 1) & 7)) << 4)) = f2bf(a[j]);
;               }
;             }
;           }
;         }
;     }
.LBB0_218:
	v_subrev_u32_e32 v196, s100, v80
	v_and_b32_e32 v197, 0x7fff, v196
	v_lshrrev_b32_e32 v196, 15, v196
	v_subrev_u32_e32 v196, s101, v196
	v_mul_u32_u24_e32 v196, 57, v196
	v_lshrrev_b32_e32 v196, 9, v196
	v_lshl_add_u32 v80, v196, 15, v197
	v_mov_b32_e32 v81, 0
	v_xor_b32_e32 v84, v130, v116
	v_lshl_add_u64 v[76:77], v[80:81], 0, v[76:77]
	v_lshlrev_b32_e32 v84, 4, v84
	v_lshl_add_u64 v[80:81], v[76:77], 0, v[0:1]
	v_and_b32_e32 v84, 0x70, v84
	v_mov_b32_e32 v85, v1
	v_xor_b32_e32 v131, v130, v117
	v_cvt_pk_bf16_f32 v72, v86, s0
	v_lshl_add_u64 v[80:81], v[80:81], 0, v[84:85]
	v_lshlrev_b32_e32 v131, 4, v131
	ds_write_b16 v80, v72
	v_cvt_pk_bf16_f32 v72, v87, s0
	v_lshl_add_u64 v[84:85], v[76:77], 0, v[6:7]
	v_and_b32_e32 v132, 0x70, v131
	v_mov_b32_e32 v133, v1
	v_xor_b32_e32 v131, v130, v122
	ds_write_b16 v80, v72 offset:128
	v_cvt_pk_bf16_f32 v72, v88, s0
	v_lshl_add_u64 v[84:85], v[84:85], 0, v[132:133]
	v_lshlrev_b32_e32 v131, 4, v131
	ds_write_b16 v84, v72
	v_lshl_add_u64 v[84:85], v[76:77], 0, v[8:9]
	v_and_b32_e32 v132, 0x70, v131
	v_cvt_pk_bf16_f32 v72, v89, s0
	v_lshl_add_u64 v[84:85], v[84:85], 0, v[132:133]
	ds_write_b16 v84, v72
	v_cvt_pk_bf16_f32 v72, v90, s0
	v_xor_b32_e32 v84, v130, v123
	ds_write_b16 v80, v72 offset:2048
	v_cvt_pk_bf16_f32 v72, v91, s0
	v_lshlrev_b32_e32 v84, 4, v84
	ds_write_b16 v80, v72 offset:2176
	v_lshl_add_u64 v[80:81], v[76:77], 0, v[10:11]
	v_and_b32_e32 v84, 0x70, v84
	v_mov_b32_e32 v85, v1
	v_cvt_pk_bf16_f32 v72, v70, s0
	v_lshl_add_u64 v[80:81], v[80:81], 0, v[84:85]
	ds_write_b16 v80, v72
	v_xor_b32_e32 v80, v130, v127
	v_lshlrev_b32_e32 v80, 4, v80
	v_lshl_add_u64 v[76:77], v[76:77], 0, v[12:13]
	v_and_b32_e32 v80, 0x70, v80
	v_mov_b32_e32 v81, v1
	v_cvt_pk_bf16_f32 v72, v71, s0
	v_lshl_add_u64 v[76:77], v[76:77], 0, v[80:81]
	ds_write_b16 v76, v72
	v_add_u32_e32 v72, 0x80, v73
	v_cmp_lt_i32_e32 vcc, s9, v72
	s_and_saveexec_b64 s[0:1], vcc
	s_xor_b64 s[0:1], exec, s[0:1]
	v_add_u32_e32 v76, 0xffffc080, v73
	v_and_b32_e32 v72, 0xcf, v72
	v_lshrrev_b32_e32 v76, 8, v76
	v_or_b32_e32 v84, 0x800, v72
	s_andn2_saveexec_b64 s[0:1], s[0:1]
	v_ashrrev_i32_e32 v76, 11, v72
	v_and_b32_e32 v84, 0x7cf, v72
	s_or_b64 exec, exec, s[0:1]
	v_lshl_or_b32 v77, v76, 1, v126
	v_lshrrev_b32_e32 v72, 6, v84
	v_mad_u64_u32 v[80:81], s[0:1], v77, 36, v[72:73]
	v_ashrrev_i32_e32 v81, 31, v80
	v_lshlrev_b64 v[80:81], 13, v[80:81]
	v_lshl_or_b32 v131, v76, 2, v126
	v_lshlrev_b32_e32 v76, 1, v84
	v_lshl_add_u64 v[80:81], s[52:53], 0, v[80:81]
	v_and_b32_e32 v76, 14, v76
	v_mov_b32_e32 v77, v1
	s_and_b64 vcc, exec, s[38:39]
	v_lshrrev_b32_e32 v130, 3, v84
	s_cbranch_vccnz .LBB0_226
	s_and_b64 vcc, exec, s[36:37]
	v_mov_b64_e32 v[84:85], v[80:81]
	s_cbranch_vccnz .LBB0_225
	v_mad_u64_u32 v[84:85], s[0:1], v131, 36, v[72:73]
	v_ashrrev_i32_e32 v85, 31, v84
	v_lshlrev_b64 v[84:85], 13, v[84:85]
	v_lshl_add_u64 v[84:85], s[54:55], 0, v[84:85]
.LBB0_225:
	v_subrev_u32_e32 v196, s100, v84
	v_and_b32_e32 v197, 0x7fff, v196
	v_lshrrev_b32_e32 v196, 15, v196
	v_subrev_u32_e32 v196, s101, v196
	v_mul_u32_u24_e32 v196, 57, v196
	v_lshrrev_b32_e32 v196, 9, v196
	v_lshl_add_u32 v84, v196, 15, v197
	v_mov_b32_e32 v85, 0
	v_xor_b32_e32 v164, v130, v116
	v_lshl_add_u64 v[84:85], v[84:85], 0, v[76:77]
	v_lshlrev_b32_e32 v164, 4, v164
	v_xor_b32_e32 v166, v130, v117
	v_lshl_add_u64 v[132:133], v[84:85], 0, v[0:1]
	v_and_b32_e32 v164, 0x70, v164
	v_mov_b32_e32 v165, v1
	v_lshlrev_b32_e32 v166, 4, v166
	v_cvt_pk_bf16_f32 v163, v64, s0
	v_lshl_add_u64 v[132:133], v[132:133], 0, v[164:165]
	v_lshl_add_u64 v[164:165], v[84:85], 0, v[6:7]
	v_and_b32_e32 v166, 0x70, v166
	v_mov_b32_e32 v167, v1
	ds_write_b16 v132, v163
	v_cvt_pk_bf16_f32 v163, v65, s0
	v_lshl_add_u64 v[164:165], v[164:165], 0, v[166:167]
	v_xor_b32_e32 v166, v130, v122
	ds_write_b16 v132, v163 offset:128
	v_cvt_pk_bf16_f32 v163, v149, s0
	v_lshlrev_b32_e32 v166, 4, v166
	ds_write_b16 v164, v163
	v_lshl_add_u64 v[164:165], v[84:85], 0, v[8:9]
	v_and_b32_e32 v166, 0x70, v166
	v_cvt_pk_bf16_f32 v163, v67, s0
	v_lshl_add_u64 v[164:165], v[164:165], 0, v[166:167]
	ds_write_b16 v164, v163
	v_cvt_pk_bf16_f32 v163, v62, s0
	v_xor_b32_e32 v164, v130, v123
	ds_write_b16 v132, v163 offset:2048
	v_cvt_pk_bf16_f32 v163, v63, s0
	v_lshlrev_b32_e32 v164, 4, v164
	ds_write_b16 v132, v163 offset:2176
	v_lshl_add_u64 v[132:133], v[84:85], 0, v[10:11]
	v_and_b32_e32 v164, 0x70, v164
	v_mov_b32_e32 v165, v1
	v_cvt_pk_bf16_f32 v163, v148, s0
	v_lshl_add_u64 v[132:133], v[132:133], 0, v[164:165]
	ds_write_b16 v132, v163
	v_xor_b32_e32 v132, v130, v127
	v_lshlrev_b32_e32 v132, 4, v132
	v_lshl_add_u64 v[84:85], v[84:85], 0, v[12:13]
	v_and_b32_e32 v132, 0x70, v132
	v_mov_b32_e32 v133, v1
	v_cvt_pk_bf16_f32 v163, v66, s0
	v_lshl_add_u64 v[84:85], v[84:85], 0, v[132:133]
	ds_write_b16 v84, v163

; DI u16 f2bf(float a) { return (u16)(pk2(a, 0.f) & 0xffffu); }
;   DI void operator()(f32x4 (&acc)[2][2][4][2], int brow, int bcol, int wr, int wc, int fr, int fq, const int nai) const {
;     ...
;     if (pn == 2 || pn == 6) {
; #pragma unroll
;       for (int ai = 0; ai < 2; ++ai)
; #pragma unroll
;         for (int m = 0; m < 4; ++m) {
;           const int row = brow + ai * 128 + wr * 64 + m * 16 + fr;
;           int b, keypos; keyof(row, b, keypos);
;           const int key = keypos & 63;
; #pragma unroll
;           for (int bj = 0; bj < 2; ++bj) {
;             if (pn == 6 && bj == 0) continue;
;             unsigned char* img = (pn == 2 ? ws + WS_VA + ((size_t)((b * 4 + bj * 2 + hsub) * 36 + (keypos >> 6))) * IMG_TILE
;                                           : ws + WS_VC + ((size_t)((b * 2 + hsub) * 36 + (keypos >> 6))) * IMG_TILE) + (key & 7) * 2;
; #pragma unroll
;             for (int n = 0; n < 2; ++n) {
;               const f32x4 a = acc[ai][bj][m][n];
; #pragma unroll
;               for (int j = 0; j < 4; ++j) {
;                 const int d = dbase + n * 16 + j;
;                 *(u16*)(img + d * 128 + ((((key >> 3)) ^ ((d >> 1) & 7)) << 4)) = f2bf(a[j]);
;               }
;             }
;           }
;         }
;     }
.LBB0_228:
	v_subrev_u32_e32 v196, s100, v80
	v_and_b32_e32 v197, 0x7fff, v196
	v_lshrrev_b32_e32 v196, 15, v196
	v_subrev_u32_e32 v196, s101, v196
	v_mul_u32_u24_e32 v196, 57, v196
	v_lshrrev_b32_e32 v196, 9, v196
	v_lshl_add_u32 v80, v196, 15, v197
	v_mov_b32_e32 v81, 0
	v_xor_b32_e32 v84, v130, v116
	v_lshl_add_u64 v[76:77], v[80:81], 0, v[76:77]
	v_lshlrev_b32_e32 v84, 4, v84
	v_lshl_add_u64 v[80:81], v[76:77], 0, v[0:1]
	v_and_b32_e32 v84, 0x70, v84
	v_mov_b32_e32 v85, v1
	v_xor_b32_e32 v131, v130, v117
	v_cvt_pk_bf16_f32 v72, v46, s0
	v_lshl_add_u64 v[80:81], v[80:81], 0, v[84:85]
	v_lshlrev_b32_e32 v131, 4, v131
	ds_write_b16 v80, v72
	v_cvt_pk_bf16_f32 v72, v47, s0
	v_lshl_add_u64 v[84:85], v[76:77], 0, v[6:7]
	v_and_b32_e32 v132, 0x70, v131
	v_mov_b32_e32 v133, v1
	v_xor_b32_e32 v131, v130, v122
	ds_write_b16 v80, v72 offset:128
	v_cvt_pk_bf16_f32 v72, v48, s0
	v_lshl_add_u64 v[84:85], v[84:85], 0, v[132:133]
	v_lshlrev_b32_e32 v131, 4, v131
	ds_write_b16 v84, v72
	v_lshl_add_u64 v[84:85], v[76:77], 0, v[8:9]
	v_and_b32_e32 v132, 0x70, v131
	v_cvt_pk_bf16_f32 v72, v49, s0
	v_lshl_add_u64 v[84:85], v[84:85], 0, v[132:133]
	ds_write_b16 v84, v72
	v_cvt_pk_bf16_f32 v72, v54, s0
	v_xor_b32_e32 v84, v130, v123
	ds_write_b16 v80, v72 offset:2048
	v_cvt_pk_bf16_f32 v72, v55, s0
	v_lshlrev_b32_e32 v84, 4, v84
	ds_write_b16 v80, v72 offset:2176
	v_lshl_add_u64 v[80:81], v[76:77], 0, v[10:11]
	v_and_b32_e32 v84, 0x70, v84
	v_mov_b32_e32 v85, v1
	v_cvt_pk_bf16_f32 v72, v56, s0
	v_lshl_add_u64 v[80:81], v[80:81], 0, v[84:85]
	ds_write_b16 v80, v72
	v_xor_b32_e32 v80, v130, v127
	v_lshlrev_b32_e32 v80, 4, v80
	v_lshl_add_u64 v[76:77], v[76:77], 0, v[12:13]
	v_and_b32_e32 v80, 0x70, v80
	v_mov_b32_e32 v81, v1
	v_cvt_pk_bf16_f32 v72, v57, s0
	v_lshl_add_u64 v[76:77], v[76:77], 0, v[80:81]
	ds_write_b16 v76, v72
	v_add_u32_e32 v72, 0x90, v73
	v_cmp_lt_i32_e32 vcc, s9, v72
	s_and_saveexec_b64 s[0:1], vcc
	s_xor_b64 s[0:1], exec, s[0:1]
	v_add_u32_e32 v76, 0xffffc090, v73
	v_and_b32_e32 v72, 0xdf, v72
	v_lshrrev_b32_e32 v76, 8, v76
	v_or_b32_e32 v84, 0x800, v72
	s_andn2_saveexec_b64 s[0:1], s[0:1]
	v_ashrrev_i32_e32 v76, 11, v72
	v_and_b32_e32 v84, 0x7df, v72
	s_or_b64 exec, exec, s[0:1]
	v_lshl_or_b32 v77, v76, 1, v126
	v_lshrrev_b32_e32 v72, 6, v84
	v_mad_u64_u32 v[80:81], s[0:1], v77, 36, v[72:73]
	v_ashrrev_i32_e32 v81, 31, v80
	v_lshlrev_b64 v[80:81], 13, v[80:81]
	v_lshl_or_b32 v131, v76, 2, v126
	v_lshlrev_b32_e32 v76, 1, v84
	v_lshl_add_u64 v[80:81], s[52:53], 0, v[80:81]
	v_and_b32_e32 v76, 14, v76
	v_mov_b32_e32 v77, v1
	s_and_b64 vcc, exec, s[38:39]
	v_lshrrev_b32_e32 v130, 3, v84
	s_cbranch_vccnz .LBB0_236
	s_and_b64 vcc, exec, s[36:37]
	v_mov_b64_e32 v[84:85], v[80:81]
	s_cbranch_vccnz .LBB0_235
	v_mad_u64_u32 v[84:85], s[0:1], v131, 36, v[72:73]
	v_ashrrev_i32_e32 v85, 31, v84
	v_lshlrev_b64 v[84:85], 13, v[84:85]
	v_lshl_add_u64 v[84:85], s[54:55], 0, v[84:85]
.LBB0_235:
	v_subrev_u32_e32 v196, s100, v84
	v_and_b32_e32 v197, 0x7fff, v196
	v_lshrrev_b32_e32 v196, 15, v196
	v_subrev_u32_e32 v196, s101, v196
	v_mul_u32_u24_e32 v196, 57, v196
	v_lshrrev_b32_e32 v196, 9, v196
	v_lshl_add_u32 v84, v196, 15, v197
	v_mov_b32_e32 v85, 0
	v_xor_b32_e32 v164, v130, v116
	v_lshl_add_u64 v[84:85], v[84:85], 0, v[76:77]
	v_lshlrev_b32_e32 v164, 4, v164
	v_xor_b32_e32 v166, v130, v117
	v_lshl_add_u64 v[132:133], v[84:85], 0, v[0:1]
	v_and_b32_e32 v164, 0x70, v164
	v_mov_b32_e32 v165, v1
	v_lshlrev_b32_e32 v166, 4, v166
	v_cvt_pk_bf16_f32 v163, v58, s0
	v_lshl_add_u64 v[132:133], v[132:133], 0, v[164:165]
	v_lshl_add_u64 v[164:165], v[84:85], 0, v[6:7]
	v_and_b32_e32 v166, 0x70, v166
	v_mov_b32_e32 v167, v1
	ds_write_b16 v132, v163
	v_cvt_pk_bf16_f32 v163, v59, s0
	v_lshl_add_u64 v[164:165], v[164:165], 0, v[166:167]
	v_xor_b32_e32 v166, v130, v122
	ds_write_b16 v132, v163 offset:128
	v_cvt_pk_bf16_f32 v163, v147, s0
	v_lshlrev_b32_e32 v166, 4, v166
	ds_write_b16 v164, v163
	v_lshl_add_u64 v[164:165], v[84:85], 0, v[8:9]
	v_and_b32_e32 v166, 0x70, v166
	v_cvt_pk_bf16_f32 v163, v61, s0
	v_lshl_add_u64 v[164:165], v[164:165], 0, v[166:167]
	ds_write_b16 v164, v163
	v_cvt_pk_bf16_f32 v163, v52, s0
	v_xor_b32_e32 v164, v130, v123
	ds_write_b16 v132, v163 offset:2048
	v_cvt_pk_bf16_f32 v163, v53, s0
	v_lshlrev_b32_e32 v164, 4, v164
	ds_write_b16 v132, v163 offset:2176
	v_lshl_add_u64 v[132:133], v[84:85], 0, v[10:11]
	v_and_b32_e32 v164, 0x70, v164
	v_mov_b32_e32 v165, v1
	v_cvt_pk_bf16_f32 v163, v146, s0
	v_lshl_add_u64 v[132:133], v[132:133], 0, v[164:165]
	ds_write_b16 v132, v163
	v_xor_b32_e32 v132, v130, v127
	v_lshlrev_b32_e32 v132, 4, v132
	v_lshl_add_u64 v[84:85], v[84:85], 0, v[12:13]
	v_and_b32_e32 v132, 0x70, v132
	v_mov_b32_e32 v133, v1
	v_cvt_pk_bf16_f32 v163, v60, s0
	v_lshl_add_u64 v[84:85], v[84:85], 0, v[132:133]
	ds_write_b16 v84, v163

; DI u16 f2bf(float a) { return (u16)(pk2(a, 0.f) & 0xffffu); }
;   DI void operator()(f32x4 (&acc)[2][2][4][2], int brow, int bcol, int wr, int wc, int fr, int fq, const int nai) const {
;     ...
;     if (pn == 2 || pn == 6) {
; #pragma unroll
;       for (int ai = 0; ai < 2; ++ai)
; #pragma unroll
;         for (int m = 0; m < 4; ++m) {
;           const int row = brow + ai * 128 + wr * 64 + m * 16 + fr;
;           int b, keypos; keyof(row, b, keypos);
;           const int key = keypos & 63;
; #pragma unroll
;           for (int bj = 0; bj < 2; ++bj) {
;             if (pn == 6 && bj == 0) continue;
;             unsigned char* img = (pn == 2 ? ws + WS_VA + ((size_t)((b * 4 + bj * 2 + hsub) * 36 + (keypos >> 6))) * IMG_TILE
;                                           : ws + WS_VC + ((size_t)((b * 2 + hsub) * 36 + (keypos >> 6))) * IMG_TILE) + (key & 7) * 2;
; #pragma unroll
;             for (int n = 0; n < 2; ++n) {
;               const f32x4 a = acc[ai][bj][m][n];
; #pragma unroll
;               for (int j = 0; j < 4; ++j) {
;                 const int d = dbase + n * 16 + j;
;                 *(u16*)(img + d * 128 + ((((key >> 3)) ^ ((d >> 1) & 7)) << 4)) = f2bf(a[j]);
;               }
;             }
;           }
;         }
;     }
.LBB0_238:
	v_subrev_u32_e32 v196, s100, v80
	v_and_b32_e32 v197, 0x7fff, v196
	v_lshrrev_b32_e32 v196, 15, v196
	v_subrev_u32_e32 v196, s101, v196
	v_mul_u32_u24_e32 v196, 57, v196
	v_lshrrev_b32_e32 v196, 9, v196
	v_lshl_add_u32 v80, v196, 15, v197
	v_mov_b32_e32 v81, 0
	v_xor_b32_e32 v84, v130, v116
	v_lshl_add_u64 v[76:77], v[80:81], 0, v[76:77]
	v_lshlrev_b32_e32 v84, 4, v84
	v_lshl_add_u64 v[80:81], v[76:77], 0, v[0:1]
	v_and_b32_e32 v84, 0x70, v84
	v_mov_b32_e32 v85, v1
	v_xor_b32_e32 v131, v130, v117
	v_cvt_pk_bf16_f32 v72, v38, s0
	v_lshl_add_u64 v[80:81], v[80:81], 0, v[84:85]
	v_lshlrev_b32_e32 v131, 4, v131
	ds_write_b16 v80, v72
	v_cvt_pk_bf16_f32 v72, v39, s0
	v_lshl_add_u64 v[84:85], v[76:77], 0, v[6:7]
	v_and_b32_e32 v132, 0x70, v131
	v_mov_b32_e32 v133, v1
	v_xor_b32_e32 v131, v130, v122
	ds_write_b16 v80, v72 offset:128
	v_cvt_pk_bf16_f32 v72, v40, s0
	v_lshl_add_u64 v[84:85], v[84:85], 0, v[132:133]
	v_lshlrev_b32_e32 v131, 4, v131
	ds_write_b16 v84, v72
	v_lshl_add_u64 v[84:85], v[76:77], 0, v[8:9]
	v_and_b32_e32 v132, 0x70, v131
	v_cvt_pk_bf16_f32 v72, v41, s0
	v_lshl_add_u64 v[84:85], v[84:85], 0, v[132:133]
	ds_write_b16 v84, v72
	v_cvt_pk_bf16_f32 v72, v42, s0
	v_xor_b32_e32 v84, v130, v123
	ds_write_b16 v80, v72 offset:2048
	v_cvt_pk_bf16_f32 v72, v43, s0
	v_lshlrev_b32_e32 v84, 4, v84
	ds_write_b16 v80, v72 offset:2176
	v_lshl_add_u64 v[80:81], v[76:77], 0, v[10:11]
	v_and_b32_e32 v84, 0x70, v84
	v_mov_b32_e32 v85, v1
	v_cvt_pk_bf16_f32 v72, v44, s0
	v_lshl_add_u64 v[80:81], v[80:81], 0, v[84:85]
	ds_write_b16 v80, v72
	v_xor_b32_e32 v80, v130, v127
	v_lshlrev_b32_e32 v80, 4, v80
	v_lshl_add_u64 v[76:77], v[76:77], 0, v[12:13]
	v_and_b32_e32 v80, 0x70, v80
	v_mov_b32_e32 v81, v1
	v_cvt_pk_bf16_f32 v72, v45, s0
	v_lshl_add_u64 v[76:77], v[76:77], 0, v[80:81]
	ds_write_b16 v76, v72
	v_add_u32_e32 v72, 0xa0, v73
	v_cmp_lt_i32_e32 vcc, s9, v72
	s_and_saveexec_b64 s[0:1], vcc
	s_xor_b64 s[0:1], exec, s[0:1]
	v_add_u32_e32 v76, 0xffffc0a0, v73
	v_and_b32_e32 v72, 0xef, v72
	v_lshrrev_b32_e32 v76, 8, v76
	v_or_b32_e32 v84, 0x800, v72
	s_andn2_saveexec_b64 s[0:1], s[0:1]
	v_ashrrev_i32_e32 v76, 11, v72
	v_and_b32_e32 v84, 0x7ef, v72
	s_or_b64 exec, exec, s[0:1]
	v_lshl_or_b32 v77, v76, 1, v126
	v_lshrrev_b32_e32 v72, 6, v84
	v_mad_u64_u32 v[80:81], s[0:1], v77, 36, v[72:73]
	v_ashrrev_i32_e32 v81, 31, v80
	v_lshlrev_b64 v[80:81], 13, v[80:81]
	v_lshl_or_b32 v131, v76, 2, v126
	v_lshlrev_b32_e32 v76, 1, v84
	v_lshl_add_u64 v[80:81], s[52:53], 0, v[80:81]
	v_and_b32_e32 v76, 14, v76
	v_mov_b32_e32 v77, v1
	s_and_b64 vcc, exec, s[38:39]
	v_lshrrev_b32_e32 v130, 3, v84
	s_cbranch_vccnz .LBB0_246
	s_and_b64 vcc, exec, s[36:37]
	v_mov_b64_e32 v[84:85], v[80:81]
	s_cbranch_vccnz .LBB0_245
	v_mad_u64_u32 v[84:85], s[0:1], v131, 36, v[72:73]
	v_ashrrev_i32_e32 v85, 31, v84
	v_lshlrev_b64 v[84:85], 13, v[84:85]
	v_lshl_add_u64 v[84:85], s[54:55], 0, v[84:85]
.LBB0_245:
	v_subrev_u32_e32 v196, s100, v84
	v_and_b32_e32 v197, 0x7fff, v196
	v_lshrrev_b32_e32 v196, 15, v196
	v_subrev_u32_e32 v196, s101, v196
	v_mul_u32_u24_e32 v196, 57, v196
	v_lshrrev_b32_e32 v196, 9, v196
	v_lshl_add_u32 v84, v196, 15, v197
	v_mov_b32_e32 v85, 0
	v_xor_b32_e32 v164, v130, v116
	v_lshl_add_u64 v[84:85], v[84:85], 0, v[76:77]
	v_lshlrev_b32_e32 v164, 4, v164
	v_xor_b32_e32 v166, v130, v117
	v_lshl_add_u64 v[132:133], v[84:85], 0, v[0:1]
	v_and_b32_e32 v164, 0x70, v164
	v_mov_b32_e32 v165, v1
	v_lshlrev_b32_e32 v166, 4, v166
	v_cvt_pk_bf16_f32 v163, v34, s0
	v_lshl_add_u64 v[132:133], v[132:133], 0, v[164:165]
	v_lshl_add_u64 v[164:165], v[84:85], 0, v[6:7]
	v_and_b32_e32 v166, 0x70, v166
	v_mov_b32_e32 v167, v1
	ds_write_b16 v132, v163
	v_cvt_pk_bf16_f32 v163, v35, s0
	v_lshl_add_u64 v[164:165], v[164:165], 0, v[166:167]
	v_xor_b32_e32 v166, v130, v122
	ds_write_b16 v132, v163 offset:128
	v_cvt_pk_bf16_f32 v163, v143, s0
	v_lshlrev_b32_e32 v166, 4, v166
	ds_write_b16 v164, v163
	v_lshl_add_u64 v[164:165], v[84:85], 0, v[8:9]
	v_and_b32_e32 v166, 0x70, v166
	v_cvt_pk_bf16_f32 v163, v51, s0
	v_lshl_add_u64 v[164:165], v[164:165], 0, v[166:167]
	ds_write_b16 v164, v163
	v_cvt_pk_bf16_f32 v163, v30, s0
	v_xor_b32_e32 v164, v130, v123
	ds_write_b16 v132, v163 offset:2048
	v_cvt_pk_bf16_f32 v163, v31, s0
	v_lshlrev_b32_e32 v164, 4, v164
	ds_write_b16 v132, v163 offset:2176
	v_lshl_add_u64 v[132:133], v[84:85], 0, v[10:11]
	v_and_b32_e32 v164, 0x70, v164
	v_mov_b32_e32 v165, v1
	v_cvt_pk_bf16_f32 v163, v142, s0
	v_lshl_add_u64 v[132:133], v[132:133], 0, v[164:165]
	ds_write_b16 v132, v163
	v_xor_b32_e32 v132, v130, v127
	v_lshlrev_b32_e32 v132, 4, v132
	v_lshl_add_u64 v[84:85], v[84:85], 0, v[12:13]
	v_and_b32_e32 v132, 0x70, v132
	v_mov_b32_e32 v133, v1
	v_cvt_pk_bf16_f32 v163, v50, s0
	v_lshl_add_u64 v[84:85], v[84:85], 0, v[132:133]
	ds_write_b16 v84, v163

; DI u16 f2bf(float a) { return (u16)(pk2(a, 0.f) & 0xffffu); }
;   DI void operator()(f32x4 (&acc)[2][2][4][2], int brow, int bcol, int wr, int wc, int fr, int fq, const int nai) const {
;     ...
;     if (pn == 2 || pn == 6) {
; #pragma unroll
;       for (int ai = 0; ai < 2; ++ai)
; #pragma unroll
;         for (int m = 0; m < 4; ++m) {
;           const int row = brow + ai * 128 + wr * 64 + m * 16 + fr;
;           int b, keypos; keyof(row, b, keypos);
;           const int key = keypos & 63;
; #pragma unroll
;           for (int bj = 0; bj < 2; ++bj) {
;             if (pn == 6 && bj == 0) continue;
;             unsigned char* img = (pn == 2 ? ws + WS_VA + ((size_t)((b * 4 + bj * 2 + hsub) * 36 + (keypos >> 6))) * IMG_TILE
;                                           : ws + WS_VC + ((size_t)((b * 2 + hsub) * 36 + (keypos >> 6))) * IMG_TILE) + (key & 7) * 2;
; #pragma unroll
;             for (int n = 0; n < 2; ++n) {
;               const f32x4 a = acc[ai][bj][m][n];
; #pragma unroll
;               for (int j = 0; j < 4; ++j) {
;                 const int d = dbase + n * 16 + j;
;                 *(u16*)(img + d * 128 + ((((key >> 3)) ^ ((d >> 1) & 7)) << 4)) = f2bf(a[j]);
;               }
;             }
;           }
;         }
;     }
.LBB0_248:
	v_subrev_u32_e32 v196, s100, v80
	v_and_b32_e32 v197, 0x7fff, v196
	v_lshrrev_b32_e32 v196, 15, v196
	v_subrev_u32_e32 v196, s101, v196
	v_mul_u32_u24_e32 v196, 57, v196
	v_lshrrev_b32_e32 v196, 9, v196
	v_lshl_add_u32 v80, v196, 15, v197
	v_mov_b32_e32 v81, 0
	v_xor_b32_e32 v84, v130, v116
	v_lshl_add_u64 v[76:77], v[80:81], 0, v[76:77]
	v_lshlrev_b32_e32 v84, 4, v84
	v_lshl_add_u64 v[80:81], v[76:77], 0, v[0:1]
	v_and_b32_e32 v84, 0x70, v84
	v_mov_b32_e32 v85, v1
	v_xor_b32_e32 v131, v130, v117
	v_cvt_pk_bf16_f32 v72, v32, s0
	v_lshl_add_u64 v[80:81], v[80:81], 0, v[84:85]
	v_lshlrev_b32_e32 v131, 4, v131
	ds_write_b16 v80, v72
	v_cvt_pk_bf16_f32 v72, v33, s0
	v_lshl_add_u64 v[84:85], v[76:77], 0, v[6:7]
	v_and_b32_e32 v132, 0x70, v131
	v_mov_b32_e32 v133, v1
	v_xor_b32_e32 v131, v130, v122
	ds_write_b16 v80, v72 offset:128
	v_cvt_pk_bf16_f32 v72, v36, s0
	v_lshl_add_u64 v[84:85], v[84:85], 0, v[132:133]
	v_lshlrev_b32_e32 v131, 4, v131
	ds_write_b16 v84, v72
	v_lshl_add_u64 v[84:85], v[76:77], 0, v[8:9]
	v_and_b32_e32 v132, 0x70, v131
	v_cvt_pk_bf16_f32 v72, v37, s0
	v_lshl_add_u64 v[84:85], v[84:85], 0, v[132:133]
	ds_write_b16 v84, v72
	v_cvt_pk_bf16_f32 v72, v18, s0
	v_xor_b32_e32 v84, v130, v123
	ds_write_b16 v80, v72 offset:2048
	v_cvt_pk_bf16_f32 v72, v19, s0
	v_lshlrev_b32_e32 v84, 4, v84
	ds_write_b16 v80, v72 offset:2176
	v_lshl_add_u64 v[80:81], v[76:77], 0, v[10:11]
	v_and_b32_e32 v84, 0x70, v84
	v_mov_b32_e32 v85, v1
	v_cvt_pk_bf16_f32 v72, v20, s0
	v_lshl_add_u64 v[80:81], v[80:81], 0, v[84:85]
	ds_write_b16 v80, v72
	v_xor_b32_e32 v80, v130, v127
	v_lshlrev_b32_e32 v80, 4, v80
	v_lshl_add_u64 v[76:77], v[76:77], 0, v[12:13]
	v_and_b32_e32 v80, 0x70, v80
	v_mov_b32_e32 v81, v1
	v_cvt_pk_bf16_f32 v72, v21, s0
	v_lshl_add_u64 v[76:77], v[76:77], 0, v[80:81]
	ds_write_b16 v76, v72
	v_add_u32_e32 v72, 0xb0, v73
	v_cmp_lt_i32_e32 vcc, s9, v72
	s_and_saveexec_b64 s[0:1], vcc
	s_xor_b64 s[0:1], exec, s[0:1]
	v_add_u32_e32 v73, 0xffffc0b0, v73
	s_movk_i32 s2, 0x800
	v_lshrrev_b32_e32 v76, 8, v73
	v_or_b32_sdwa v84, v72, s2 dst_sel:DWORD dst_unused:UNUSED_PAD src0_sel:BYTE_0 src1_sel:DWORD
	s_andn2_saveexec_b64 s[0:1], s[0:1]
	v_ashrrev_i32_e32 v76, 11, v72
	v_and_b32_e32 v84, 0x7ff, v72
	s_or_b64 exec, exec, s[0:1]
	v_lshl_or_b32 v73, v76, 1, v126
	v_lshrrev_b32_e32 v72, 6, v84
	v_mad_u64_u32 v[80:81], s[0:1], v73, 36, v[72:73]
	v_ashrrev_i32_e32 v81, 31, v80
	v_lshlrev_b64 v[80:81], 13, v[80:81]
	v_lshlrev_b32_e32 v73, 1, v84
	v_lshl_add_u64 v[80:81], s[52:53], 0, v[80:81]
	v_lshl_or_b32 v126, v76, 2, v126
	v_and_b32_e32 v76, 14, v73
	v_mov_b32_e32 v77, v1
	s_and_b64 vcc, exec, s[38:39]
	v_lshrrev_b32_e32 v73, 3, v84
	s_cbranch_vccnz .LBB0_256
	s_and_b64 vcc, exec, s[36:37]
	v_mov_b64_e32 v[84:85], v[80:81]
	s_cbranch_vccnz .LBB0_255
	v_mad_u64_u32 v[84:85], s[0:1], v126, 36, v[72:73]
	v_ashrrev_i32_e32 v85, 31, v84
	v_lshlrev_b64 v[84:85], 13, v[84:85]
	v_lshl_add_u64 v[84:85], s[54:55], 0, v[84:85]
.LBB0_255:
	v_subrev_u32_e32 v196, s100, v84
	v_and_b32_e32 v197, 0x7fff, v196
	v_lshrrev_b32_e32 v196, 15, v196
	v_subrev_u32_e32 v196, s101, v196
	v_mul_u32_u24_e32 v196, 57, v196
	v_lshrrev_b32_e32 v196, 9, v196
	v_lshl_add_u32 v84, v196, 15, v197
	v_mov_b32_e32 v85, 0
	v_xor_b32_e32 v132, v73, v116
	v_lshl_add_u64 v[84:85], v[84:85], 0, v[76:77]
	v_lshlrev_b32_e32 v132, 4, v132
	v_lshl_add_u64 v[130:131], v[84:85], 0, v[0:1]
	v_and_b32_e32 v132, 0x70, v132
	v_mov_b32_e32 v133, v1
	v_xor_b32_e32 v164, v73, v117
	v_lshl_add_u64 v[130:131], v[130:131], 0, v[132:133]
	v_cvt_pk_bf16_f32 v132, v27, s0
	v_lshlrev_b32_e32 v164, 4, v164
	ds_write_b16 v130, v132 offset:128
	v_lshl_add_u64 v[132:133], v[84:85], 0, v[6:7]
	v_and_b32_e32 v164, 0x70, v164
	v_mov_b32_e32 v165, v1
	v_cvt_pk_bf16_f32 v163, v26, s0
	v_lshl_add_u64 v[132:133], v[132:133], 0, v[164:165]
	v_xor_b32_e32 v164, v73, v122
	ds_write_b16 v130, v163
	v_cvt_pk_bf16_f32 v163, v5, s0
	v_lshlrev_b32_e32 v164, 4, v164
	ds_write_b16 v132, v163
	v_lshl_add_u64 v[132:133], v[84:85], 0, v[8:9]
	v_and_b32_e32 v164, 0x70, v164
	v_cvt_pk_bf16_f32 v163, v29, s0
	v_lshl_add_u64 v[132:133], v[132:133], 0, v[164:165]
	ds_write_b16 v132, v163
	v_cvt_pk_bf16_f32 v132, v22, s0
	ds_write_b16 v130, v132 offset:2048
	v_cvt_pk_bf16_f32 v132, v23, s0
	ds_write_b16 v130, v132 offset:2176
	v_xor_b32_e32 v132, v73, v123
	v_lshlrev_b32_e32 v132, 4, v132
	v_lshl_add_u64 v[130:131], v[84:85], 0, v[10:11]
	v_and_b32_e32 v132, 0x70, v132
	v_mov_b32_e32 v133, v1
	v_cvt_pk_bf16_f32 v163, v4, s0
	v_lshl_add_u64 v[130:131], v[130:131], 0, v[132:133]
	ds_write_b16 v130, v163
	v_xor_b32_e32 v130, v73, v127
	v_lshlrev_b32_e32 v130, 4, v130
	v_lshl_add_u64 v[84:85], v[84:85], 0, v[12:13]
	v_and_b32_e32 v130, 0x70, v130
	v_mov_b32_e32 v131, v1
	v_cvt_pk_bf16_f32 v132, v28, s0
	v_lshl_add_u64 v[84:85], v[84:85], 0, v[130:131]
	ds_write_b16 v84, v132

; DI u16 f2bf(float a) { return (u16)(pk2(a, 0.f) & 0xffffu); }
;   DI void operator()(f32x4 (&acc)[2][2][4][2], int brow, int bcol, int wr, int wc, int fr, int fq, const int nai) const {
;     ...
;     if (pn == 2 || pn == 6) {
; #pragma unroll
;       for (int ai = 0; ai < 2; ++ai)
; #pragma unroll
;         for (int m = 0; m < 4; ++m) {
;           const int row = brow + ai * 128 + wr * 64 + m * 16 + fr;
;           int b, keypos; keyof(row, b, keypos);
;           const int key = keypos & 63;
; #pragma unroll
;           for (int bj = 0; bj < 2; ++bj) {
;             if (pn == 6 && bj == 0) continue;
;             unsigned char* img = (pn == 2 ? ws + WS_VA + ((size_t)((b * 4 + bj * 2 + hsub) * 36 + (keypos >> 6))) * IMG_TILE
;                                           : ws + WS_VC + ((size_t)((b * 2 + hsub) * 36 + (keypos >> 6))) * IMG_TILE) + (key & 7) * 2;
; #pragma unroll
;             for (int n = 0; n < 2; ++n) {
;               const f32x4 a = acc[ai][bj][m][n];
; #pragma unroll
;               for (int j = 0; j < 4; ++j) {
;                 const int d = dbase + n * 16 + j;
;                 *(u16*)(img + d * 128 + ((((key >> 3)) ^ ((d >> 1) & 7)) << 4)) = f2bf(a[j]);
;               }
;             }
;           }
;         }
;     }
.LBB0_258:
	v_subrev_u32_e32 v196, s100, v80
	v_and_b32_e32 v197, 0x7fff, v196
	v_lshrrev_b32_e32 v196, 15, v196
	v_subrev_u32_e32 v196, s101, v196
	v_mul_u32_u24_e32 v196, 57, v196
	v_lshrrev_b32_e32 v196, 9, v196
	v_lshl_add_u32 v80, v196, 15, v197
	v_mov_b32_e32 v81, 0
	v_lshl_add_u64 v[76:77], v[80:81], 0, v[76:77]
	v_lshl_add_u64 v[80:81], v[76:77], 0, v[0:1]
	v_xor_b32_e32 v0, v73, v116
	v_lshlrev_b32_e32 v0, 4, v0
	v_and_b32_e32 v0, 0x70, v0
	v_lshl_add_u64 v[80:81], v[80:81], 0, v[0:1]
	v_cvt_pk_bf16_f32 v0, v3, s0
	ds_write_b16 v80, v0 offset:128
	v_xor_b32_e32 v0, v73, v117
	v_lshlrev_b32_e32 v0, 4, v0
	v_lshl_add_u64 v[6:7], v[76:77], 0, v[6:7]
	v_and_b32_e32 v0, 0x70, v0
	v_cvt_pk_bf16_f32 v72, v2, s0
	v_lshl_add_u64 v[6:7], v[6:7], 0, v[0:1]
	v_xor_b32_e32 v0, v73, v122
	ds_write_b16 v80, v72
	v_cvt_pk_bf16_f32 v72, v24, s0
	v_lshlrev_b32_e32 v0, 4, v0
	ds_write_b16 v6, v72
	v_lshl_add_u64 v[6:7], v[76:77], 0, v[8:9]
	v_and_b32_e32 v0, 0x70, v0
	v_lshl_add_u64 v[6:7], v[6:7], 0, v[0:1]
	v_cvt_pk_bf16_f32 v0, v14, s0
	ds_write_b16 v80, v0 offset:2048
	v_cvt_pk_bf16_f32 v0, v15, s0
	ds_write_b16 v80, v0 offset:2176
	v_xor_b32_e32 v0, v73, v123
	v_cvt_pk_bf16_f32 v72, v25, s0
	v_lshlrev_b32_e32 v0, 4, v0
	ds_write_b16 v6, v72
	v_lshl_add_u64 v[6:7], v[76:77], 0, v[10:11]
	v_and_b32_e32 v0, 0x70, v0
	v_lshl_add_u64 v[6:7], v[6:7], 0, v[0:1]
	v_xor_b32_e32 v0, v73, v127
	v_cvt_pk_bf16_f32 v8, v16, s0
	v_lshlrev_b32_e32 v0, 4, v0
	ds_write_b16 v6, v8
	v_lshl_add_u64 v[6:7], v[76:77], 0, v[12:13]
	v_and_b32_e32 v0, 0x70, v0
	v_cvt_pk_bf16_f32 v8, v17, s0
	v_lshl_add_u64 v[6:7], v[6:7], 0, v[0:1]
	ds_write_b16 v6, v8
	s_waitcnt lgkmcnt(0)
	s_barrier
	v_mbcnt_lo_u32_b32 v196, -1, 0
	v_mbcnt_hi_u32_b32 v196, -1, v196
	v_or_b32_e32 v196, s90, v196
	v_lshlrev_b32_e32 v198, 4, v196
	v_mov_b32_e32 v199, v198
	s_cmp_eq_u32 s23, 2
	s_cselect_b64 s[0:1], s[54:55], s[52:53]
	s_cselect_b32 s63, 4, 2
	s_lshl_b32 s62, s101, 15
	s_add_u32 s0, s0, s62
	s_addc_u32 s1, s1, 0
	s_mov_b32 s62, 0
.Lvt_copy:
	ds_read_b128 v[200:203], v199
	ds_read_b128 v[204:207], v199 offset:8192
	ds_read_b128 v[208:211], v199 offset:16384
	ds_read_b128 v[212:215], v199 offset:24576
	s_waitcnt lgkmcnt(3)
	global_store_dwordx4 v198, v[200:203], s[0:1]
	s_add_u32 s0, s0, 0x2000
	s_addc_u32 s1, s1, 0
	s_waitcnt lgkmcnt(2)
	global_store_dwordx4 v198, v[204:207], s[0:1]
	s_add_u32 s0, s0, 0x2000
	s_addc_u32 s1, s1, 0
	s_waitcnt lgkmcnt(1)
	global_store_dwordx4 v198, v[208:211], s[0:1]
	s_add_u32 s0, s0, 0x2000
	s_addc_u32 s1, s1, 0
	s_waitcnt lgkmcnt(0)
	global_store_dwordx4 v198, v[212:215], s[0:1]
	s_add_u32 s0, s0, 0x42000
	s_addc_u32 s1, s1, 0
	v_add_u32_e32 v199, 0x8000, v199
	s_add_i32 s62, s62, 1
	s_cmp_lt_u32 s62, s63
	s_cbranch_scc1 .Lvt_copy
